# P0: scalar fast path around per-store win_col exec-mask chain for interior n-blocks (6 of 8 store blocks); plus M4 norm-weight loads hoisted out of token loop; plus vmcnt(0) at GEMM unit start dropped
# speedup vs baseline: 1.0017x; 1.0017x over previous
.LBB0_33:
	s_lshl_b32 s15, s16, 3
	s_load_dwordx2 s[28:29], s[94:95], s15 offset:0x0
	s_and_b64 s[30:31], s[18:19], exec
	s_cselect_b32 s15, s24, 0
	s_mul_i32 s15, s15, s26
	s_lshl_b32 s15, s15, 2
	s_waitcnt lgkmcnt(0)
	s_add_u32 s21, s28, s15
	s_addc_u32 s25, s29, 0
	s_lshr_b32 s15, s26, 6
	v_cvt_f32_u32_e32 v6, s15
	s_add_i32 s27, s27, s17
	s_sub_i32 s17, 0, s15
	s_add_i32 s16, s3, s27
	v_rcp_iflag_f32_e32 v6, v6
	s_abs_i32 s27, s16
	s_ashr_i32 s24, s16, 31
	v_mul_f32_e32 v6, 0x4f7ffffe, v6
	v_cvt_u32_f32_e32 v6, v6
	s_nop 0
	v_readfirstlane_b32 s28, v6
	s_mul_i32 s17, s17, s28
	s_mul_hi_u32 s17, s28, s17
	s_add_i32 s28, s28, s17
	s_mul_hi_u32 s17, s27, s28
	s_mul_i32 s28, s17, s15
	s_sub_i32 s27, s27, s28
	s_add_i32 s29, s17, 1
	s_sub_i32 s28, s27, s15
	s_cmp_ge_u32 s27, s15
	s_cselect_b32 s17, s29, s17
	s_cselect_b32 s27, s28, s27
	s_add_i32 s28, s17, 1
	s_cmp_ge_u32 s27, s15
	s_cselect_b32 s17, s28, s17
	s_xor_b32 s17, s17, s24
	s_sub_i32 s17, s17, s24
	s_mul_i32 s15, s17, s15
	s_sub_i32 s15, s16, s15
	s_lshl_b32 s16, s15, 6
	s_mov_b32 s101, 0
	s_cmp_ge_u32 s16, 0x1040
	s_cselect_b32 s101, -16, s101
	s_cmp_ge_u32 s16, 0x1840
	s_cselect_b32 s101, 0xffffffe0, s101
	s_cmp_ge_u32 s16, 0x3040
	s_cselect_b32 s101, 0xffffffc0, s101
	s_cmp_eq_u32 s16, 0x1000
	s_cselect_b32 s101, 1, s101
	s_cmp_eq_u32 s16, 0x1800
	s_cselect_b32 s101, 1, s101
	s_cmp_eq_u32 s16, 0x3000
	s_cselect_b32 s101, 1, s101
	s_lshl_b32 s24, s17, 6
	s_ashr_i32 s17, s16, 31
	s_lshl_b64 s[28:29], s[16:17], 2
	v_or_b32_e32 v57, s24, v16
	s_add_u32 s28, s21, s28
	s_addc_u32 s29, s25, s29
	v_or_b32_e32 v8, 4, v57
	v_or_b32_e32 v58, 8, v57
	v_or_b32_e32 v60, 12, v57
	v_or_b32_e32 v66, 16, v57
	v_or_b32_e32 v68, 20, v57
	v_or_b32_e32 v74, 24, v57
	v_or_b32_e32 v76, 28, v57
	v_or_b32_e32 v82, 32, v57
	v_or_b32_e32 v84, 36, v57
	v_or_b32_e32 v90, 40, v57
	v_or_b32_e32 v92, 44, v57
	v_or_b32_e32 v94, 48, v57
	v_or_b32_e32 v100, 52, v57
	v_lshl_add_u64 v[14:15], s[28:29], 0, v[4:5]
	v_mad_i64_i32 v[6:7], s[28:29], v57, s26, 0
	v_mad_i64_i32 v[8:9], s[28:29], v8, s26, 0
	v_mad_i64_i32 v[58:59], s[28:29], v58, s26, 0
	v_mad_i64_i32 v[60:61], s[28:29], v60, s26, 0
	v_mad_i64_i32 v[66:67], s[28:29], v66, s26, 0
	v_mad_i64_i32 v[68:69], s[28:29], v68, s26, 0
	v_mad_i64_i32 v[74:75], s[28:29], v74, s26, 0
	v_mad_i64_i32 v[76:77], s[28:29], v76, s26, 0
	v_mad_i64_i32 v[82:83], s[28:29], v82, s26, 0
	v_mad_i64_i32 v[84:85], s[28:29], v84, s26, 0
	v_mad_i64_i32 v[90:91], s[28:29], v90, s26, 0
	v_mad_i64_i32 v[92:93], s[28:29], v92, s26, 0
	v_mad_i64_i32 v[94:95], s[28:29], v94, s26, 0
	v_mad_i64_i32 v[100:101], s[28:29], v100, s26, 0
	v_lshl_add_u64 v[6:7], v[6:7], 2, v[14:15]
	v_lshl_add_u64 v[10:11], v[8:9], 2, v[14:15]
	v_lshl_add_u64 v[58:59], v[58:59], 2, v[14:15]
	v_lshl_add_u64 v[62:63], v[60:61], 2, v[14:15]
	v_lshl_add_u64 v[66:67], v[66:67], 2, v[14:15]
	v_lshl_add_u64 v[70:71], v[68:69], 2, v[14:15]
	v_lshl_add_u64 v[74:75], v[74:75], 2, v[14:15]
	v_lshl_add_u64 v[78:79], v[76:77], 2, v[14:15]
	v_lshl_add_u64 v[82:83], v[82:83], 2, v[14:15]
	v_lshl_add_u64 v[86:87], v[84:85], 2, v[14:15]
	v_lshl_add_u64 v[90:91], v[90:91], 2, v[14:15]
	v_lshl_add_u64 v[96:97], v[92:93], 2, v[14:15]
	v_lshl_add_u64 v[98:99], v[94:95], 2, v[14:15]
	v_lshl_add_u64 v[102:103], v[100:101], 2, v[14:15]
	global_load_dwordx4 v[6:9], v[6:7], off nt
	s_nop 0
	global_load_dwordx4 v[10:13], v[10:11], off nt
	s_nop 0
	global_load_dwordx4 v[58:61], v[58:59], off nt
	s_nop 0
	global_load_dwordx4 v[62:65], v[62:63], off nt
	s_nop 0
	global_load_dwordx4 v[66:69], v[66:67], off nt
	s_nop 0
	global_load_dwordx4 v[70:73], v[70:71], off nt
	s_nop 0
	global_load_dwordx4 v[74:77], v[74:75], off nt
	s_nop 0
	global_load_dwordx4 v[78:81], v[78:79], off nt
	s_nop 0
	global_load_dwordx4 v[82:85], v[82:83], off nt
	s_nop 0
	global_load_dwordx4 v[86:89], v[86:87], off nt
	s_nop 0
	global_load_dwordx4 v[90:93], v[90:91], off nt
	s_nop 0
	global_load_dwordx4 v[94:97], v[96:97], off nt
	s_nop 0
	global_load_dwordx4 v[98:101], v[98:99], off nt
	s_nop 0
	global_load_dwordx4 v[102:105], v[102:103], off nt
	v_or_b32_e32 v106, 56, v57
	v_mad_i64_i32 v[106:107], s[28:29], v106, s26, 0
	v_lshl_add_u64 v[106:107], v[106:107], 2, v[14:15]
	v_or_b32_e32 v57, 60, v57
	v_mad_i64_i32 v[110:111], s[26:27], v57, s26, 0
	global_load_dwordx4 v[106:109], v[106:107], off nt
	v_lshl_add_u64 v[14:15], v[110:111], 2, v[14:15]
	global_load_dwordx4 v[110:113], v[14:15], off nt
	v_add_u32_e32 v57, 0x400, v18
	s_lshl_b32 s15, s15, 7
	s_cmp_lt_i32 s12, 2
	s_mov_b64 s[26:27], -1
	s_waitcnt vmcnt(15)
	ds_write2_b32 v26, v6, v7 offset1:1
	ds_write2_b32 v26, v8, v9 offset0:2 offset1:3
	s_waitcnt vmcnt(14)
	ds_write2_b32 v27, v10, v11 offset1:1
	ds_write2_b32 v28, v12, v13 offset1:1
	s_waitcnt vmcnt(13)
	ds_write2_b32 v29, v58, v59 offset1:1
	ds_write2_b32 v30, v60, v61 offset1:1
	s_waitcnt vmcnt(12)
	ds_write2_b32 v31, v62, v63 offset1:1
	ds_write2_b32 v32, v64, v65 offset1:1
	s_waitcnt vmcnt(11)
	ds_write2_b32 v33, v66, v67 offset1:1
	ds_write2_b32 v34, v68, v69 offset1:1
	s_waitcnt vmcnt(10)
	ds_write2_b32 v35, v70, v71 offset1:1
	ds_write2_b32 v36, v72, v73 offset1:1
	s_waitcnt vmcnt(9)
	ds_write2_b32 v37, v74, v75 offset1:1
	ds_write2_b32 v38, v76, v77 offset1:1
	s_waitcnt vmcnt(8)
	ds_write2_b32 v39, v78, v79 offset1:1
	ds_write2_b32 v40, v80, v81 offset1:1
	s_waitcnt vmcnt(7)
	ds_write2_b32 v41, v82, v83 offset1:1
	ds_write2_b32 v42, v84, v85 offset1:1
	s_waitcnt vmcnt(6)
	ds_write2_b32 v43, v86, v87 offset1:1
	ds_write2_b32 v44, v88, v89 offset1:1
	s_waitcnt vmcnt(5)
	ds_write2_b32 v45, v90, v91 offset1:1
	ds_write2_b32 v46, v92, v93 offset1:1
	s_waitcnt vmcnt(4)
	ds_write2_b32 v47, v94, v95 offset1:1
	ds_write2_b32 v48, v96, v97 offset1:1
	s_waitcnt vmcnt(3)
	ds_write2_b32 v49, v98, v99 offset1:1
	ds_write2_b32 v50, v100, v101 offset1:1
	s_waitcnt vmcnt(2)
	ds_write2_b32 v51, v102, v103 offset1:1
	ds_write2_b32 v52, v104, v105 offset1:1
	s_waitcnt vmcnt(1)
	ds_write2_b32 v53, v106, v107 offset1:1
	ds_write2_b32 v54, v108, v109 offset1:1
	s_waitcnt vmcnt(0)
	ds_write2_b32 v55, v110, v111 offset1:1
	ds_write2_b32 v56, v112, v113 offset1:1
	s_waitcnt lgkmcnt(0)
	ds_read2_b32 v[8:9], v18 offset1:65
	ds_read2_b32 v[10:11], v18 offset0:130 offset1:195
	ds_read2_b32 v[12:13], v57 offset0:4 offset1:69
	ds_read2_b32 v[14:15], v57 offset0:134 offset1:199
	v_or_b32_e32 v6, s16, v17
	s_cbranch_scc1 .LBB0_80
	s_cmp_gt_i32 s12, 2
	s_cbranch_scc0 .LBB0_77
	v_cmp_lt_i32_e32 vcc, s47, v6
	v_mov_b32_e32 v58, v6
	s_and_saveexec_b64 s[26:27], vcc
	s_cbranch_execz .LBB0_76
	s_cmpk_gt_u32 s16, 0x1007
	s_mov_b64 s[28:29], -1
	s_cbranch_scc0 .LBB0_74
	s_cmpk_gt_u32 s16, 0x100f
	s_cbranch_scc0 .LBB0_71
	s_cmpk_gt_u32 s16, 0x120f
	s_cbranch_scc0 .LBB0_68
	s_cmpk_gt_u32 s16, 0x140f
	s_cbranch_scc0 .LBB0_65
	s_cmpk_gt_u32 s16, 0x180f
	s_cbranch_scc0 .LBB0_62
	s_cmpk_gt_u32 s16, 0x181f
	s_cbranch_scc0 .LBB0_59
	s_cmpk_gt_u32 s16, 0x1c1f
	s_cbranch_scc0 .LBB0_56
	s_cmpk_gt_u32 s16, 0x241f
	s_cbranch_scc0 .LBB0_53
	s_cmpk_gt_u32 s16, 0x301f
	s_cbranch_scc0 .LBB0_50
	s_cmpk_gt_u32 s16, 0x303f
	s_cbranch_scc0 .LBB0_47
	v_subrev_u32_e32 v58, 64, v6
	s_mov_b64 s[28:29], 0

.LBB0_84:
	s_and_b64 s[18:19], s[18:19], exec
	s_cselect_b32 s17, 0xe300000, 0
	s_add_u32 s17, s42, s17
	s_addc_u32 s18, s43, 0
	s_add_u32 s17, s17, s22
	s_addc_u32 s18, s18, s23
	s_lshl_b32 s19, s20, 1
	s_add_u32 s17, s17, s19
	s_addc_u32 s20, s18, 0
	s_ashr_i32 s25, s24, 31
	s_lshl_b64 s[18:19], s[24:25], 1
	s_add_u32 s18, s17, s18
	s_addc_u32 s19, s20, s19
	v_lshl_add_u64 v[6:7], s[18:19], 0, v[2:3]
	s_waitcnt lgkmcnt(3)
	v_cvt_pk_bf16_f32 v8, v8, v9
	s_waitcnt lgkmcnt(2)
	v_cvt_pk_bf16_f32 v9, v10, v11
	s_waitcnt lgkmcnt(1)
	v_cvt_pk_bf16_f32 v10, v12, v13
	v_mad_i64_i32 v[12:13], s[18:19], s14, v58, 0
	s_waitcnt lgkmcnt(0)
	v_cvt_pk_bf16_f32 v11, v14, v15
	v_lshl_add_u64 v[12:13], v[12:13], 1, v[6:7]
	global_store_dwordx4 v[12:13], v[8:11], off
	ds_read2_b32 v[8:9], v18 offset0:8 offset1:73
	ds_read2_b32 v[10:11], v18 offset0:138 offset1:203
	ds_read2_b32 v[12:13], v57 offset0:12 offset1:77
	ds_read2_b32 v[14:15], v57 offset0:142 offset1:207
	v_or_b32_e32 v58, s16, v19
	s_cmp_lt_i32 s12, 2
	s_mov_b64 s[18:19], -1
	s_cbranch_scc1 .LBB0_131
	s_cmp_gt_i32 s12, 2
	s_cbranch_scc0 .LBB0_128
	s_cmp_eq_u32 s101, 1
	s_cbranch_scc1 .Lp0_slow_0
	v_add_u32_e32 v59, s101, v58
	s_branch .LBB0_135
.Lp0_slow_0:
	v_cmp_lt_i32_e32 vcc, s47, v58
	v_mov_b32_e32 v59, v58
	s_and_saveexec_b64 s[18:19], vcc
	s_cbranch_execz .LBB0_127
	v_cmp_lt_u32_e32 vcc, s48, v58
	s_and_saveexec_b64 s[20:21], vcc
	s_xor_b64 s[20:21], exec, s[20:21]
	s_cbranch_execz .LBB0_124
	s_cmpk_lt_u32 s16, 0x1010
	s_mov_b64 s[22:23], -1
	s_cbranch_scc1 .LBB0_122
	s_cmpk_lt_u32 s16, 0x1210
	s_cbranch_scc1 .LBB0_119
	s_cmpk_lt_u32 s16, 0x1410
	s_cbranch_scc1 .LBB0_116
	s_cmpk_lt_u32 s16, 0x1810
	s_cbranch_scc1 .LBB0_113
	s_cmpk_lt_u32 s16, 0x1820
	s_cbranch_scc1 .LBB0_110
	s_cmpk_lt_u32 s16, 0x1c20
	s_cbranch_scc1 .LBB0_107
	s_cmpk_lt_u32 s16, 0x2420
	s_cbranch_scc1 .LBB0_104
	s_cmpk_lt_u32 s16, 0x3020
	s_cbranch_scc1 .LBB0_101
	s_cmpk_lt_u32 s16, 0x3040
	s_cbranch_scc1 .LBB0_98
	v_subrev_u32_e32 v59, 64, v58
	s_mov_b64 s[22:23], 0

.LBB0_135:
	s_waitcnt lgkmcnt(3)
	v_cvt_pk_bf16_f32 v8, v8, v9
	s_waitcnt lgkmcnt(2)
	v_cvt_pk_bf16_f32 v9, v10, v11
	s_waitcnt lgkmcnt(1)
	v_cvt_pk_bf16_f32 v10, v12, v13
	v_mad_i64_i32 v[12:13], s[18:19], s14, v59, 0
	s_waitcnt lgkmcnt(0)
	v_cvt_pk_bf16_f32 v11, v14, v15
	v_lshl_add_u64 v[12:13], v[12:13], 1, v[6:7]
	global_store_dwordx4 v[12:13], v[8:11], off
	ds_read2_b32 v[8:9], v18 offset0:16 offset1:81
	ds_read2_b32 v[10:11], v18 offset0:146 offset1:211
	ds_read2_b32 v[12:13], v57 offset0:20 offset1:85
	ds_read2_b32 v[14:15], v57 offset0:150 offset1:215
	v_or_b32_e32 v58, s16, v20
	s_cmp_lt_i32 s12, 2
	s_mov_b64 s[18:19], -1
	s_cbranch_scc1 .LBB0_182
	s_cmp_gt_i32 s12, 2
	s_cbranch_scc0 .LBB0_179
	s_cmp_eq_u32 s101, 1
	s_cbranch_scc1 .Lp0_slow_1
	v_add_u32_e32 v59, s101, v58
	s_branch .LBB0_186
.Lp0_slow_1:
	v_cmp_lt_i32_e32 vcc, s47, v58
	v_mov_b32_e32 v59, v58
	s_and_saveexec_b64 s[18:19], vcc
	s_cbranch_execz .LBB0_178
	v_cmp_lt_u32_e32 vcc, s48, v58
	s_and_saveexec_b64 s[20:21], vcc
	s_xor_b64 s[20:21], exec, s[20:21]
	s_cbranch_execz .LBB0_175
	v_cmp_lt_u32_e32 vcc, s49, v58
	s_and_saveexec_b64 s[22:23], vcc
	s_xor_b64 s[22:23], exec, s[22:23]
	s_cbranch_execz .LBB0_172
	v_cmp_lt_u32_e32 vcc, s50, v58
	s_and_saveexec_b64 s[24:25], vcc
	s_xor_b64 s[24:25], exec, s[24:25]
	s_cbranch_execz .LBB0_169
	v_cmp_lt_u32_e32 vcc, s51, v58
	s_and_saveexec_b64 s[26:27], vcc
	s_xor_b64 s[26:27], exec, s[26:27]
	s_cbranch_execz .LBB0_166
	v_cmp_lt_u32_e32 vcc, s52, v58
	s_and_saveexec_b64 s[28:29], vcc
	s_xor_b64 s[28:29], exec, s[28:29]
	s_cbranch_execz .LBB0_163
	s_cmpk_lt_u32 s16, 0x1820
	s_mov_b64 s[30:31], -1
	s_cbranch_scc1 .LBB0_161
	s_cmpk_lt_u32 s16, 0x1c20
	s_cbranch_scc1 .LBB0_158
	s_cmpk_lt_u32 s16, 0x2420
	s_cbranch_scc1 .LBB0_155
	s_cmpk_lt_u32 s16, 0x3020
	s_cbranch_scc1 .LBB0_152
	s_cmpk_lt_u32 s16, 0x3040
	s_cbranch_scc1 .LBB0_149
	v_subrev_u32_e32 v59, 64, v58
	s_mov_b64 s[30:31], 0

.LBB0_186:
	s_waitcnt lgkmcnt(3)
	v_cvt_pk_bf16_f32 v8, v8, v9
	s_waitcnt lgkmcnt(2)
	v_cvt_pk_bf16_f32 v9, v10, v11
	s_waitcnt lgkmcnt(1)
	v_cvt_pk_bf16_f32 v10, v12, v13
	v_mad_i64_i32 v[12:13], s[18:19], s14, v59, 0
	s_waitcnt lgkmcnt(0)
	v_cvt_pk_bf16_f32 v11, v14, v15
	v_lshl_add_u64 v[12:13], v[12:13], 1, v[6:7]
	global_store_dwordx4 v[12:13], v[8:11], off
	ds_read2_b32 v[8:9], v18 offset0:24 offset1:89
	ds_read2_b32 v[10:11], v18 offset0:154 offset1:219
	ds_read2_b32 v[12:13], v57 offset0:28 offset1:93
	ds_read2_b32 v[14:15], v57 offset0:158 offset1:223
	v_or_b32_e32 v58, s16, v21
	s_cmp_lt_i32 s12, 2
	s_mov_b64 s[18:19], -1
	s_cbranch_scc1 .LBB0_233
	s_cmp_gt_i32 s12, 2
	s_cbranch_scc0 .LBB0_230
	s_cmp_eq_u32 s101, 1
	s_cbranch_scc1 .Lp0_slow_2
	v_add_u32_e32 v59, s101, v58
	s_branch .LBB0_237

.LBB0_237:
	s_waitcnt lgkmcnt(3)
	v_cvt_pk_bf16_f32 v8, v8, v9
	s_waitcnt lgkmcnt(2)
	v_cvt_pk_bf16_f32 v9, v10, v11
	s_waitcnt lgkmcnt(1)
	v_cvt_pk_bf16_f32 v10, v12, v13
	v_mad_i64_i32 v[12:13], s[18:19], s14, v59, 0
	s_waitcnt lgkmcnt(0)
	v_cvt_pk_bf16_f32 v11, v14, v15
	v_lshl_add_u64 v[12:13], v[12:13], 1, v[6:7]
	global_store_dwordx4 v[12:13], v[8:11], off
	ds_read2_b32 v[8:9], v18 offset0:32 offset1:97
	ds_read2_b32 v[10:11], v18 offset0:162 offset1:227
	ds_read2_b32 v[12:13], v57 offset0:36 offset1:101
	ds_read2_b32 v[14:15], v57 offset0:166 offset1:231
	v_or_b32_e32 v58, s16, v22
	s_cmp_lt_i32 s12, 2
	s_mov_b64 s[18:19], -1
	s_cbranch_scc1 .LBB0_284
	s_cmp_gt_i32 s12, 2
	s_cbranch_scc0 .LBB0_281
	s_cmp_eq_u32 s101, 1
	s_cbranch_scc1 .Lp0_slow_3
	v_add_u32_e32 v59, s101, v58
	s_branch .LBB0_288
.Lp0_slow_3:
	v_cmp_lt_i32_e32 vcc, s47, v58
	v_mov_b32_e32 v59, v58
	s_and_saveexec_b64 s[18:19], vcc
	s_cbranch_execz .LBB0_280
	v_cmp_lt_u32_e32 vcc, s48, v58
	s_and_saveexec_b64 s[20:21], vcc
	s_xor_b64 s[20:21], exec, s[20:21]
	s_cbranch_execz .LBB0_277
	v_cmp_lt_u32_e32 vcc, s49, v58
	s_and_saveexec_b64 s[22:23], vcc
	s_xor_b64 s[22:23], exec, s[22:23]
	s_cbranch_execz .LBB0_274
	v_cmp_lt_u32_e32 vcc, s50, v58
	s_and_saveexec_b64 s[24:25], vcc
	s_xor_b64 s[24:25], exec, s[24:25]
	s_cbranch_execz .LBB0_271
	v_cmp_lt_u32_e32 vcc, s51, v58
	s_and_saveexec_b64 s[26:27], vcc
	s_xor_b64 s[26:27], exec, s[26:27]
	s_cbranch_execz .LBB0_268
	v_cmp_lt_u32_e32 vcc, s52, v58
	s_and_saveexec_b64 s[28:29], vcc
	s_xor_b64 s[28:29], exec, s[28:29]
	s_cbranch_execz .LBB0_265
	v_cmp_lt_u32_e32 vcc, s53, v58
	s_and_saveexec_b64 s[30:31], vcc
	s_xor_b64 s[30:31], exec, s[30:31]
	s_cbranch_execz .LBB0_262
	v_cmp_lt_u32_e32 vcc, s55, v58
	s_and_saveexec_b64 s[34:35], vcc
	s_xor_b64 s[34:35], exec, s[34:35]
	s_cbranch_execz .LBB0_259
	v_cmp_lt_u32_e32 vcc, s56, v58
	s_and_saveexec_b64 s[36:37], vcc
	s_xor_b64 s[36:37], exec, s[36:37]
	s_cbranch_execz .LBB0_256
	v_cmp_lt_u32_e32 vcc, s57, v58
	s_and_saveexec_b64 s[38:39], vcc
	s_xor_b64 s[38:39], exec, s[38:39]
	s_cbranch_execz .LBB0_253
	s_cmpk_lt_u32 s16, 0x3040
	s_mov_b64 s[40:41], -1
	s_cbranch_scc1 .LBB0_251
	v_subrev_u32_e32 v59, 64, v58
	s_mov_b64 s[40:41], 0

.LBB0_288:
	s_waitcnt lgkmcnt(3)
	v_cvt_pk_bf16_f32 v8, v8, v9
	s_waitcnt lgkmcnt(2)
	v_cvt_pk_bf16_f32 v9, v10, v11
	s_waitcnt lgkmcnt(1)
	v_cvt_pk_bf16_f32 v10, v12, v13
	v_mad_i64_i32 v[12:13], s[18:19], s14, v59, 0
	s_waitcnt lgkmcnt(0)
	v_cvt_pk_bf16_f32 v11, v14, v15
	v_lshl_add_u64 v[12:13], v[12:13], 1, v[6:7]
	global_store_dwordx4 v[12:13], v[8:11], off
	ds_read2_b32 v[8:9], v18 offset0:40 offset1:105
	ds_read2_b32 v[10:11], v18 offset0:170 offset1:235
	ds_read2_b32 v[12:13], v57 offset0:44 offset1:109
	ds_read2_b32 v[14:15], v57 offset0:174 offset1:239
	v_or_b32_e32 v58, s16, v23
	s_cmp_lt_i32 s12, 2
	s_mov_b64 s[18:19], -1
	s_cbranch_scc1 .LBB0_335
	s_cmp_gt_i32 s12, 2
	s_cbranch_scc0 .LBB0_332
	s_cmp_eq_u32 s101, 1
	s_cbranch_scc1 .Lp0_slow_4
	v_add_u32_e32 v59, s101, v58
	s_branch .LBB0_339

.LBB0_339:
	s_waitcnt lgkmcnt(3)
	v_cvt_pk_bf16_f32 v8, v8, v9
	s_waitcnt lgkmcnt(2)
	v_cvt_pk_bf16_f32 v9, v10, v11
	s_waitcnt lgkmcnt(1)
	v_cvt_pk_bf16_f32 v10, v12, v13
	v_mad_i64_i32 v[12:13], s[18:19], s14, v59, 0
	s_waitcnt lgkmcnt(0)
	v_cvt_pk_bf16_f32 v11, v14, v15
	v_lshl_add_u64 v[12:13], v[12:13], 1, v[6:7]
	global_store_dwordx4 v[12:13], v[8:11], off
	ds_read2_b32 v[8:9], v18 offset0:48 offset1:113
	ds_read2_b32 v[10:11], v18 offset0:178 offset1:243
	ds_read2_b32 v[12:13], v57 offset0:52 offset1:117
	ds_read2_b32 v[14:15], v57 offset0:182 offset1:247
	v_or_b32_e32 v58, s16, v24
	s_cmp_lt_i32 s12, 2
	s_mov_b64 s[18:19], -1
	s_cbranch_scc1 .LBB0_386
	s_cmp_gt_i32 s12, 2
	s_cbranch_scc0 .LBB0_383
	s_cmp_eq_u32 s101, 1
	s_cbranch_scc1 .Lp0_slow_5
	v_add_u32_e32 v59, s101, v58
	s_branch .LBB0_390

	.amdhsa_kernel _Z6mk_fwd4Args
		.amdhsa_group_segment_fixed_size 0
		.amdhsa_private_segment_fixed_size 0
		.amdhsa_kernarg_size 592
		.amdhsa_user_sgpr_count 2
		.amdhsa_user_sgpr_dispatch_ptr 0
		.amdhsa_user_sgpr_queue_ptr 0
		.amdhsa_user_sgpr_kernarg_segment_ptr 1
		.amdhsa_user_sgpr_dispatch_id 0
		.amdhsa_user_sgpr_kernarg_preload_length 0
		.amdhsa_user_sgpr_kernarg_preload_offset 0
		.amdhsa_user_sgpr_private_segment_size 0
		.amdhsa_uses_dynamic_stack 0
		.amdhsa_enable_private_segment 0
		.amdhsa_system_sgpr_workgroup_id_x 1
		.amdhsa_system_sgpr_workgroup_id_y 0
		.amdhsa_system_sgpr_workgroup_id_z 0
		.amdhsa_system_sgpr_workgroup_info 0
		.amdhsa_system_vgpr_workitem_id 0
		.amdhsa_next_free_vgpr 256
		.amdhsa_next_free_sgpr 102
		.amdhsa_accum_offset 256
		.amdhsa_reserve_vcc 1
		.amdhsa_float_round_mode_32 0
		.amdhsa_float_round_mode_16_64 0
		.amdhsa_float_denorm_mode_32 3
		.amdhsa_float_denorm_mode_16_64 3
		.amdhsa_dx10_clamp 1
		.amdhsa_ieee_mode 1
		.amdhsa_fp16_overflow 0
		.amdhsa_tg_split 0
		.amdhsa_exception_fp_ieee_invalid_op 0
		.amdhsa_exception_fp_denorm_src 0
		.amdhsa_exception_fp_ieee_div_zero 0
		.amdhsa_exception_fp_ieee_overflow 0
		.amdhsa_exception_fp_ieee_underflow 0
		.amdhsa_exception_fp_ieee_inexact 0
		.amdhsa_exception_int_div_zero 0
	.end_amdhsa_kernel

amdhsa.kernels:
  - .agpr_count:     0
    .args:
      - .offset:         0
        .size:           336
        .value_kind:     by_value
      - .offset:         336
        .size:           4
        .value_kind:     hidden_block_count_x
      - .offset:         340
        .size:           4
        .value_kind:     hidden_block_count_y
      - .offset:         344
        .size:           4
        .value_kind:     hidden_block_count_z
      - .offset:         348
        .size:           2
        .value_kind:     hidden_group_size_x
      - .offset:         350
        .size:           2
        .value_kind:     hidden_group_size_y
      - .offset:         352
        .size:           2
        .value_kind:     hidden_group_size_z
      - .offset:         354
        .size:           2
        .value_kind:     hidden_remainder_x
      - .offset:         356
        .size:           2
        .value_kind:     hidden_remainder_y
      - .offset:         358
        .size:           2
        .value_kind:     hidden_remainder_z
      - .offset:         376
        .size:           8
        .value_kind:     hidden_global_offset_x
      - .offset:         384
        .size:           8
        .value_kind:     hidden_global_offset_y
      - .offset:         392
        .size:           8
        .value_kind:     hidden_global_offset_z
      - .offset:         400
        .size:           2
        .value_kind:     hidden_grid_dims
      - .offset:         456
        .size:           4
        .value_kind:     hidden_dynamic_lds_size
    .group_segment_fixed_size: 0
    .kernarg_segment_align: 8
    .kernarg_segment_size: 592
    .language:       OpenCL C
    .language_version:
      - 2
      - 0
    .max_flat_workgroup_size: 512
    .name:           _Z6mk_fwd4Args
    .private_segment_fixed_size: 0
    .sgpr_count:     108
    .sgpr_spill_count: 241
    .symbol:         _Z6mk_fwd4Args.kd
    .uniform_work_group_size: 1
    .uses_dynamic_stack: false
    .vgpr_count:     256
    .vgpr_spill_count: 0
    .wavefront_size: 64
